# v78 + final RMSNorm rows remapped to the owning row panel so MLP-down(layer 3) -> final norm is a 4-workgroup hand-off (no attention point-to-point hand-off: FB aliases Q/K/V)
# speedup vs baseline: 1.0260x; 1.0029x over previous
.LBB0_2087:
	v_readlane_b32 s100, v255, 8
	s_bitcmp1_b32 s100, 0
	s_cbranch_scc0 .Lgs_orig_5
	s_waitcnt vmcnt(0) lgkmcnt(0)
	s_barrier
	v_readlane_b32 s100, v255, 59
	s_add_i32 s100, s100, 1
	v_writelane_b32 v255, s100, 59
	v_cmp_eq_u32_e32 vcc, 0, v215
	s_and_saveexec_b64 s[0:1], vcc
	s_cbranch_execz .Lgs_w_5
	s_load_dwordx2 s[2:3], s[94:95], 0xb8
	v_readlane_b32 s101, v255, 12
	s_and_b32 s101, s101, 63
	s_lshl_b32 s101, s101, 6
	s_cmp_lt_u32 s101, 0x800
	s_movk_i32 s7, 0x1400
	s_cselect_b32 s7, 0xc00, s7
	s_add_i32 s101, s101, s7
	s_lshl_b32 s100, s100, 2
	v_mov_b32_e32 v0, s101
	v_mov_b32_e32 v1, 1
	s_waitcnt lgkmcnt(0)
	s_add_u32 s2, s2, 0xe0000
	s_addc_u32 s3, s3, 0
	global_atomic_add v0, v1, s[2:3]
	buffer_inv sc1
	s_mov_b32 s6, 0

; __device__ __forceinline__ float bf_lo(unsigned w) { return __uint_as_float(w << 16); }
; __device__ __forceinline__ float bf_hi(unsigned w) { return __uint_as_float(w & 0xffff0000u); }
; __global__ void __launch_bounds__(NWAVES * 64, 2) fwd_kernel(Args args) {
;     ...
;     PHASE_BEGIN
;     {
;         f32x4 g4[4];
; #pragma unroll
;         for (int j = 0; j < 4; ++j) g4[j] = *(const f32x4*)(A_->final_g + 4 * lane + 256 * j);
;         for (int row = gw; row < MLAT; row += 2 * NGW) {
;             const int rowb = row + NGW < MLAT ? row + NGW : row;
;             const unsigned long long* ha = (const unsigned long long*)(H16 + (size_t)row * DM) + lane; const unsigned long long* hb_ = (const unsigned long long*)(H16 + (size_t)rowb * DM) + lane;
;             unsigned long long ra[4], rb[4];
; #pragma unroll
;             for (int j = 0; j < 4; ++j) { ra[j] = ha[64 * j]; rb[j] = hb_[64 * j]; }
;             f32x4 va[4], vb[4]; float sa = 0.f, sb = 0.f;
; #pragma unroll
;             for (int j = 0; j < 4; ++j) { const unsigned al = (unsigned)ra[j], ah = (unsigned)(ra[j] >> 32), bl = (unsigned)rb[j], bh = (unsigned)(rb[j] >> 32);
;                 va[j] = (f32x4){bf_lo(al), bf_hi(al), bf_lo(ah), bf_hi(ah)}; vb[j] = (f32x4){bf_lo(bl), bf_hi(bl), bf_lo(bh), bf_hi(bh)};
;                 sa += (va[j][0] * va[j][0] + va[j][1] * va[j][1]) + (va[j][2] * va[j][2] + va[j][3] * va[j][3]);
;                 sb += (vb[j][0] * vb[j][0] + vb[j][1] * vb[j][1]) + (vb[j][2] * vb[j][2] + vb[j][3] * vb[j][3]); }
; #pragma unroll
;             for (int o = 1; o < 64; o <<= 1) { sa += __shfl_xor(sa, o); sb += __shfl_xor(sb, o); }
;             const float rsa = rsqrtf(sa * (1.f / DM) + EPS), rsb = rsqrtf(sb * (1.f / DM) + EPS);
;             f32x4* oa = (f32x4*)(A_->out + (size_t)row * DM) + lane; f32x4* ob = (f32x4*)(A_->out + (size_t)rowb * DM) + lane;
; #pragma unroll
;             for (int j = 0; j < 4; ++j) { oa[64 * j] = va[j] * rsa * g4[j]; ob[64 * j] = vb[j] * rsb * g4[j]; }
;         }
.LBB0_2161:
	v_readlane_b32 s2, v254, 2
	s_cmp_le_i32 s80, s2
	s_cselect_b64 s[0:1], -1, 0
	s_cmp_lt_i32 s2, s81
	s_cselect_b64 s[2:3], -1, 0
	s_and_b64 s[0:1], s[0:1], s[2:3]
	s_and_b64 vcc, exec, s[0:1]
	s_cbranch_vccz .LBB0_2231
	s_waitcnt vmcnt(0)
	v_mov_b32_e32 v0, v215
	s_lshl_b32 s1, s84, 3
	v_readfirstlane_b32 s0, v0
	s_ashr_i32 s0, s0, 6
	s_waitcnt lgkmcnt(0)
	s_lshl_b32 s6, s0, 3
	s_and_b32 s100, s84, 7
	s_lshl_b32 s100, s100, 3
	s_bfe_u32 s101, s84, 0x30003
	s_add_i32 s100, s100, s101
	s_lshl_b32 s100, s100, 8
	s_add_i32 s6, s6, s100
	s_lshr_b32 s100, s84, 6
	s_lshl_b32 s100, s100, 6
	s_add_i32 s6, s6, s100
	s_add_i32 s101, s6, 8
	s_cmpk_gt_i32 s6, 0x3fff
	s_cbranch_scc1 .LBB0_2165
	s_load_dwordx2 s[0:1], s[94:95], 0xa8
	s_load_dwordx4 s[8:11], s[94:95], 0xb0
	v_and_b32_e32 v16, 63, v0
	v_lshlrev_b32_e32 v18, 4, v16
	v_lshlrev_b32_e32 v20, 3, v16
	s_waitcnt lgkmcnt(0)
	global_load_dwordx4 v[0:3], v18, s[0:1]
	global_load_dwordx4 v[4:7], v18, s[0:1] offset:1024
	global_load_dwordx4 v[8:11], v18, s[0:1] offset:2048
	global_load_dwordx4 v[12:15], v18, s[0:1] offset:3072
	v_mov_b32_e32 v21, 0
	v_and_b32_e32 v19, 64, v246
	v_lshl_add_u64 v[16:17], s[10:11], 0, v[20:21]
	v_add_u32_e32 v20, 64, v19
	v_mov_b32_e32 v19, v21
	v_xor_b32_e32 v21, 1, v246
	v_cmp_lt_i32_e32 vcc, v21, v20
	v_xor_b32_e32 v22, 2, v246
	v_xor_b32_e32 v23, 4, v246
	v_cndmask_b32_e32 v21, v246, v21, vcc
	v_cmp_lt_i32_e32 vcc, v22, v20
	v_xor_b32_e32 v24, 8, v246
	v_xor_b32_e32 v25, 16, v246
	v_cndmask_b32_e32 v22, v246, v22, vcc
	v_cmp_lt_i32_e32 vcc, v23, v20
	v_xor_b32_e32 v26, 32, v246
	s_mov_b64 s[0:1], 0x14200000
	v_cndmask_b32_e32 v23, v246, v23, vcc
	v_cmp_lt_i32_e32 vcc, v24, v20
	s_mov_b32 s3, 1
	v_lshl_add_u64 v[16:17], v[16:17], 0, s[0:1]
	v_cndmask_b32_e32 v24, v246, v24, vcc
	v_cmp_lt_i32_e32 vcc, v25, v20
	v_lshl_add_u64 v[18:19], s[8:9], 0, v[18:19]
	v_lshlrev_b32_e32 v21, 2, v21
	v_cndmask_b32_e32 v25, v246, v25, vcc
	v_cmp_lt_i32_e32 vcc, v26, v20
	v_lshlrev_b32_e32 v22, 2, v22
	v_lshlrev_b32_e32 v23, 2, v23
	v_cndmask_b32_e32 v20, v246, v26, vcc
	v_lshlrev_b32_e32 v24, 2, v24
	v_lshlrev_b32_e32 v25, 2, v25
	v_lshlrev_b32_e32 v26, 2, v20
	s_mov_b32 s2, 0x3a800000
	v_mov_b32_e32 v20, 0x358637bd
	s_mov_b32 s4, 0x800000
.LBB0_2164:
	s_add_i32 s5, s6, s3
	s_cmpk_lt_i32 s5, 0x4000
	s_cselect_b32 s0, s5, s6
	s_ashr_i32 s7, s6, 31
	s_lshl_b64 s[8:9], s[6:7], 11
	s_ashr_i32 s1, s0, 31
	v_lshl_add_u64 v[28:29], v[16:17], 0, s[8:9]
	s_lshl_b64 s[8:9], s[0:1], 11
	global_load_dwordx2 v[30:31], v[28:29], off
	global_load_dwordx2 v[32:33], v[28:29], off offset:512
	global_load_dwordx2 v[34:35], v[28:29], off offset:1024
	s_nop 0
	global_load_dwordx2 v[28:29], v[28:29], off offset:1536
	v_lshl_add_u64 v[36:37], v[16:17], 0, s[8:9]
	global_load_dwordx2 v[38:39], v[36:37], off
	global_load_dwordx2 v[40:41], v[36:37], off offset:512
	global_load_dwordx2 v[42:43], v[36:37], off offset:1024
	s_nop 0
	global_load_dwordx2 v[36:37], v[36:37], off offset:1536
	s_lshl_b64 s[0:1], s[0:1], 12
	v_lshl_add_u64 v[62:63], v[18:19], 0, s[0:1]
	s_lshl_b64 s[10:11], s[6:7], 12
	s_add_i32 s6, s5, s3
	v_lshl_add_u64 v[60:61], v[18:19], 0, s[10:11]
	s_cmp_ge_i32 s6, s101
	s_waitcnt vmcnt(7)
	v_lshlrev_b32_e32 v44, 16, v30
	v_and_b32_e32 v45, 0xffff0000, v30
	v_lshlrev_b32_e32 v30, 16, v31
	v_and_b32_e32 v31, 0xffff0000, v31
	s_waitcnt vmcnt(6)
	v_lshlrev_b32_e32 v46, 16, v32
	v_and_b32_e32 v47, 0xffff0000, v32
	v_lshlrev_b32_e32 v32, 16, v33
	v_and_b32_e32 v33, 0xffff0000, v33
	v_mov_b32_e32 v56, v45
	v_mov_b32_e32 v57, v31
	s_waitcnt vmcnt(3)
	v_lshlrev_b32_e32 v52, 16, v38
	v_and_b32_e32 v53, 0xffff0000, v38
	v_lshlrev_b32_e32 v38, 16, v39
	v_and_b32_e32 v39, 0xffff0000, v39
	v_mov_b32_e32 v54, v44
	v_mov_b32_e32 v55, v30
	s_waitcnt vmcnt(2)
	v_lshlrev_b32_e32 v58, 16, v40
	v_and_b32_e32 v59, 0xffff0000, v40
	v_lshlrev_b32_e32 v40, 16, v41
	v_and_b32_e32 v41, 0xffff0000, v41
	v_mov_b32_e32 v66, v47
	v_mov_b32_e32 v67, v33
	v_pk_mul_f32 v[56:57], v[56:57], v[56:57]
	v_lshlrev_b32_e32 v48, 16, v34
	v_and_b32_e32 v49, 0xffff0000, v34
	v_lshlrev_b32_e32 v34, 16, v35
	v_and_b32_e32 v35, 0xffff0000, v35
	v_mov_b32_e32 v64, v46
	v_mov_b32_e32 v65, v32
	v_mul_f32_e32 v27, v53, v53
	v_mul_f32_e32 v80, v39, v39
	v_pk_mul_f32 v[66:67], v[66:67], v[66:67]
	v_mul_f32_e32 v81, v59, v59
	v_mul_f32_e32 v82, v41, v41
	v_pk_fma_f32 v[54:55], v[54:55], v[54:55], v[56:57]
	v_lshlrev_b32_e32 v50, 16, v28
	v_and_b32_e32 v51, 0xffff0000, v28
	v_lshlrev_b32_e32 v28, 16, v29
	v_and_b32_e32 v29, 0xffff0000, v29
	v_mul_f32_e32 v70, v49, v49
	v_mul_f32_e32 v72, v35, v35
	v_fmac_f32_e32 v27, v52, v52
	v_fmac_f32_e32 v80, v38, v38
	v_pk_fma_f32 v[56:57], v[64:65], v[64:65], v[66:67]
	v_fmac_f32_e32 v81, v58, v58
	v_fmac_f32_e32 v82, v40, v40
	v_pk_add_f32 v[54:55], v[54:55], v[54:55] op_sel:[0,1] op_sel_hi:[1,0]
	s_waitcnt vmcnt(1)
; __device__ __forceinline__ float bf_lo(unsigned w) { return __uint_as_float(w << 16); }
; __device__ __forceinline__ float bf_hi(unsigned w) { return __uint_as_float(w & 0xffff0000u); }
; __global__ void __launch_bounds__(NWAVES * 64, 2) fwd_kernel(Args args) {
;     ...
; #pragma unroll
;             for (int j = 0; j < 4; ++j) { ra[j] = ha[64 * j]; rb[j] = hb_[64 * j]; }
;             f32x4 va[4], vb[4]; float sa = 0.f, sb = 0.f;
; #pragma unroll
;             for (int j = 0; j < 4; ++j) { const unsigned al = (unsigned)ra[j], ah = (unsigned)(ra[j] >> 32), bl = (unsigned)rb[j], bh = (unsigned)(rb[j] >> 32);
;                 va[j] = (f32x4){bf_lo(al), bf_hi(al), bf_lo(ah), bf_hi(ah)}; vb[j] = (f32x4){bf_lo(bl), bf_hi(bl), bf_lo(bh), bf_hi(bh)};
;                 sa += (va[j][0] * va[j][0] + va[j][1] * va[j][1]) + (va[j][2] * va[j][2] + va[j][3] * va[j][3]);
;                 sb += (vb[j][0] * vb[j][0] + vb[j][1] * vb[j][1]) + (vb[j][2] * vb[j][2] + vb[j][3] * vb[j][3]); }
; #pragma unroll
;             for (int o = 1; o < 64; o <<= 1) { sa += __shfl_xor(sa, o); sb += __shfl_xor(sb, o); }
;             const float rsa = rsqrtf(sa * (1.f / DM) + EPS), rsb = rsqrtf(sb * (1.f / DM) + EPS);
;             f32x4* oa = (f32x4*)(A_->out + (size_t)row * DM) + lane; f32x4* ob = (f32x4*)(A_->out + (size_t)rowb * DM) + lane;
; #pragma unroll
;             for (int j = 0; j < 4; ++j) { oa[64 * j] = va[j] * rsa * g4[j]; ob[64 * j] = vb[j] * rsb * g4[j]; }
;         }
	v_lshlrev_b32_e32 v68, 16, v42
	v_and_b32_e32 v69, 0xffff0000, v42
	v_lshlrev_b32_e32 v42, 16, v43
	v_and_b32_e32 v43, 0xffff0000, v43
	v_pk_mul_f32 v[76:77], v[50:51], v[50:51]
	v_pk_mul_f32 v[78:79], v[28:29], v[28:29]
	v_pk_fma_f32 v[70:71], v[48:49], v[48:49], v[70:71] op_sel_hi:[1,1,0]
	v_pk_fma_f32 v[72:73], v[34:35], v[34:35], v[72:73] op_sel_hi:[1,1,0]
	v_add_f32_e32 v27, v27, v80
	v_pk_add_f32 v[56:57], v[56:57], v[56:57] op_sel:[0,1] op_sel_hi:[1,0]
	v_add_f32_e32 v55, v81, v82
	s_waitcnt vmcnt(0)
	v_lshlrev_b32_e32 v74, 16, v36
	v_and_b32_e32 v75, 0xffff0000, v36
	v_lshlrev_b32_e32 v36, 16, v37
	v_and_b32_e32 v37, 0xffff0000, v37
	v_mul_f32_e32 v83, v69, v69
	v_mul_f32_e32 v84, v43, v43
	v_mov_b32_e32 v71, v78
	v_mov_b32_e32 v73, v79
	v_add_f32_e32 v27, v27, v55
	v_mov_b32_e32 v55, v76
	v_mov_b32_e32 v57, v77
	v_mul_f32_e32 v85, v75, v75
	v_mul_f32_e32 v86, v37, v37
	v_fmac_f32_e32 v83, v68, v68
	v_fmac_f32_e32 v84, v42, v42
	v_pk_add_f32 v[64:65], v[70:71], v[72:73]
	v_pk_add_f32 v[54:55], v[54:55], v[56:57]
	v_fmac_f32_e32 v85, v74, v74
	v_fmac_f32_e32 v86, v36, v36
	v_add_f32_e32 v67, v83, v84
	v_pk_add_f32 v[54:55], v[54:55], v[64:65]
	v_add_f32_e32 v66, v85, v86
	v_add_f32_e32 v70, v27, v67
	v_mov_b32_e32 v71, v54
	v_mov_b32_e32 v67, v55
	v_pk_add_f32 v[54:55], v[70:71], v[66:67]
	ds_bpermute_b32 v57, v21, v55
	ds_bpermute_b32 v56, v21, v54
	s_waitcnt lgkmcnt(0)
	v_pk_add_f32 v[54:55], v[54:55], v[56:57]
	ds_bpermute_b32 v57, v22, v55
	ds_bpermute_b32 v56, v22, v54
	s_waitcnt lgkmcnt(0)
	v_pk_add_f32 v[54:55], v[54:55], v[56:57]
	ds_bpermute_b32 v57, v23, v55
	ds_bpermute_b32 v56, v23, v54
	s_waitcnt lgkmcnt(0)
	v_pk_add_f32 v[54:55], v[54:55], v[56:57]
	ds_bpermute_b32 v57, v24, v55
	ds_bpermute_b32 v56, v24, v54
	s_waitcnt lgkmcnt(0)
	v_pk_add_f32 v[54:55], v[54:55], v[56:57]
	ds_bpermute_b32 v57, v25, v55
	ds_bpermute_b32 v56, v25, v54
	s_waitcnt lgkmcnt(0)
	v_pk_add_f32 v[54:55], v[54:55], v[56:57]
	ds_bpermute_b32 v57, v26, v55
	ds_bpermute_b32 v56, v26, v54
	s_waitcnt lgkmcnt(0)
	v_pk_add_f32 v[54:55], v[54:55], v[56:57]
	s_nop 0
	v_pk_fma_f32 v[54:55], v[54:55], s[2:3], v[20:21] op_sel_hi:[1,0,0]
	s_nop 0
	v_mul_f32_e32 v27, 0x4b800000, v55
	v_cmp_gt_f32_e64 s[0:1], s4, v55
	v_mul_f32_e32 v56, 0x4b800000, v54
	v_cmp_gt_f32_e32 vcc, s4, v54
	v_cndmask_b32_e64 v27, v55, v27, s[0:1]
	v_rsq_f32_e32 v27, v27
	v_cndmask_b32_e32 v54, v54, v56, vcc
	v_rsq_f32_e32 v55, v54
	v_mul_f32_e32 v54, 0x45800000, v27
	v_cndmask_b32_e64 v54, v27, v54, s[0:1]
	v_mul_f32_e32 v56, 0x45800000, v55
	v_cndmask_b32_e32 v56, v55, v56, vcc
	v_pk_mul_f32 v[44:45], v[54:55], v[44:45] op_sel_hi:[0,1]
	v_pk_mul_f32 v[30:31], v[54:55], v[30:31] op_sel_hi:[0,1]
	v_pk_mul_f32 v[52:53], v[56:57], v[52:53] op_sel_hi:[0,1]
	v_pk_mul_f32 v[38:39], v[56:57], v[38:39] op_sel_hi:[0,1]
	v_pk_mul_f32 v[46:47], v[54:55], v[46:47] op_sel_hi:[0,1]
	v_pk_mul_f32 v[64:65], v[54:55], v[32:33] op_sel_hi:[0,1]
	v_pk_mul_f32 v[58:59], v[56:57], v[58:59] op_sel_hi:[0,1]
	v_pk_mul_f32 v[40:41], v[56:57], v[40:41] op_sel_hi:[0,1]
	v_pk_mul_f32 v[48:49], v[54:55], v[48:49] op_sel_hi:[0,1]
	v_pk_mul_f32 v[66:67], v[54:55], v[34:35] op_sel_hi:[0,1]
	v_pk_mul_f32 v[68:69], v[56:57], v[68:69] op_sel_hi:[0,1]
	v_pk_mul_f32 v[70:71], v[56:57], v[42:43] op_sel_hi:[0,1]
	v_pk_mul_f32 v[72:73], v[54:55], v[50:51] op_sel_hi:[0,1]
	v_pk_mul_f32 v[54:55], v[54:55], v[28:29] op_sel_hi:[0,1]
	v_pk_mul_f32 v[74:75], v[56:57], v[74:75] op_sel_hi:[0,1]
	v_pk_mul_f32 v[56:57], v[56:57], v[36:37] op_sel_hi:[0,1]
	v_pk_mul_f32 v[30:31], v[30:31], v[2:3]
	v_pk_mul_f32 v[28:29], v[44:45], v[0:1]
	v_pk_mul_f32 v[34:35], v[2:3], v[38:39]
	v_pk_mul_f32 v[32:33], v[0:1], v[52:53]
	v_pk_mul_f32 v[38:39], v[64:65], v[6:7]
	v_pk_mul_f32 v[36:37], v[46:47], v[4:5]
	v_pk_mul_f32 v[42:43], v[6:7], v[40:41]
	v_pk_mul_f32 v[40:41], v[4:5], v[58:59]
	v_pk_mul_f32 v[46:47], v[66:67], v[10:11]
	v_pk_mul_f32 v[44:45], v[48:49], v[8:9]
	v_pk_mul_f32 v[50:51], v[10:11], v[70:71]
	v_pk_mul_f32 v[48:49], v[8:9], v[68:69]
	v_pk_mul_f32 v[54:55], v[54:55], v[14:15]
	v_pk_mul_f32 v[52:53], v[72:73], v[12:13]
	v_pk_mul_f32 v[58:59], v[14:15], v[56:57]
	v_pk_mul_f32 v[56:57], v[12:13], v[74:75]
	global_store_dwordx4 v[60:61], v[28:31], off
	global_store_dwordx4 v[62:63], v[32:35], off
	global_store_dwordx4 v[60:61], v[36:39], off offset:1024
	global_store_dwordx4 v[62:63], v[40:43], off offset:1024
	global_store_dwordx4 v[60:61], v[44:47], off offset:2048
	global_store_dwordx4 v[62:63], v[48:51], off offset:2048
	global_store_dwordx4 v[60:61], v[52:55], off offset:3072
	global_store_dwordx4 v[62:63], v[56:59], off offset:3072
	s_cbranch_scc0 .LBB0_2164
